# second static mixers item made XCD-contiguous (adjacent pool/rglru tiles on one XCD)
# baseline (speedup 1.0000x reference)
.LBB0_577:
	v_sub_f32_e32 v1, v37, v0
	v_exp_f32_e32 v1, v1
	v_sub_f32_e32 v3, v45, v0
	v_exp_f32_e32 v3, v3
	s_waitcnt vmcnt(12)
	v_sub_f32_e32 v4, v47, v0
	v_exp_f32_e32 v4, v4
	v_sub_f32_e32 v5, v46, v0
	v_exp_f32_e32 v5, v5
	v_sub_f32_e32 v6, v8, v0
	v_add_f32_e32 v2, v1, v39
	v_exp_f32_e32 v6, v6
	v_sub_f32_e32 v7, v9, v0
	v_add_f32_e32 v2, v3, v2
	v_exp_f32_e32 v7, v7
	v_sub_f32_e32 v8, v10, v0
	v_add_f32_e32 v2, v4, v2
	v_exp_f32_e32 v8, v8
	v_sub_f32_e32 v9, v11, v0
	v_add_f32_e32 v2, v5, v2
	v_exp_f32_e32 v9, v9
	v_sub_f32_e32 v10, v12, v0
	v_add_f32_e32 v2, v6, v2
	v_exp_f32_e32 v10, v10
	v_sub_f32_e32 v11, v13, v0
	v_add_f32_e32 v2, v7, v2
	v_exp_f32_e32 v11, v11
	v_sub_f32_e32 v12, v14, v0
	v_add_f32_e32 v2, v8, v2
	v_exp_f32_e32 v36, v12
	v_sub_f32_e32 v12, v15, v0
	v_add_f32_e32 v2, v9, v2
	v_exp_f32_e32 v15, v12
	v_sub_f32_e32 v12, v16, v0
	v_add_f32_e32 v2, v10, v2
	v_exp_f32_e32 v37, v12
	v_sub_f32_e32 v12, v17, v0
	v_add_f32_e32 v2, v11, v2
	v_exp_f32_e32 v38, v12
	v_sub_f32_e32 v12, v18, v0
	v_add_f32_e32 v2, v36, v2
	v_exp_f32_e32 v39, v12
	v_sub_f32_e32 v12, v19, v0
	v_add_f32_e32 v2, v15, v2
	v_exp_f32_e32 v45, v12
	v_sub_f32_e32 v12, v20, v0
	v_add_f32_e32 v2, v37, v2
	v_exp_f32_e32 v20, v12
	v_sub_f32_e32 v12, v21, v0
	v_add_f32_e32 v2, v38, v2
	v_exp_f32_e32 v21, v12
	v_sub_f32_e32 v12, v22, v0
	v_add_f32_e32 v2, v39, v2
	v_exp_f32_e32 v22, v12
	v_sub_f32_e32 v12, v23, v0
	v_add_f32_e32 v2, v45, v2
	v_exp_f32_e32 v23, v12
	v_sub_f32_e32 v12, v24, v0
	v_add_f32_e32 v2, v20, v2
	v_exp_f32_e32 v24, v12
	v_sub_f32_e32 v12, v25, v0
	v_add_f32_e32 v2, v21, v2
	v_exp_f32_e32 v25, v12
	v_sub_f32_e32 v12, v26, v0
	v_add_f32_e32 v2, v22, v2
	v_exp_f32_e32 v26, v12
	v_sub_f32_e32 v12, v27, v0
	v_add_f32_e32 v2, v23, v2
	v_exp_f32_e32 v27, v12
	v_sub_f32_e32 v12, v28, v0
	v_add_f32_e32 v2, v24, v2
	v_exp_f32_e32 v28, v12
	v_sub_f32_e32 v12, v29, v0
	v_add_f32_e32 v2, v25, v2
	v_exp_f32_e32 v29, v12
	v_sub_f32_e32 v12, v30, v0
	v_add_f32_e32 v2, v26, v2
	v_exp_f32_e32 v30, v12
	v_sub_f32_e32 v12, v31, v0
	v_add_f32_e32 v2, v27, v2
	v_exp_f32_e32 v31, v12
	v_sub_f32_e32 v12, v32, v0
	v_add_f32_e32 v2, v28, v2
	v_exp_f32_e32 v32, v12
	v_sub_f32_e32 v12, v33, v0
	v_add_f32_e32 v2, v29, v2
	v_exp_f32_e32 v33, v12
	v_sub_f32_e32 v12, v34, v0
	v_add_f32_e32 v2, v30, v2
	v_exp_f32_e32 v34, v12
	v_sub_f32_e32 v12, v35, v0
	v_add_f32_e32 v2, v31, v2
	v_exp_f32_e32 v35, v12
	v_sub_f32_e32 v12, v41, v0
	v_add_f32_e32 v2, v32, v2
	v_exp_f32_e32 v41, v12
	v_sub_f32_e32 v12, v40, v0
	v_add_f32_e32 v2, v33, v2
	v_exp_f32_e32 v40, v12
	v_sub_f32_e32 v12, v43, v0
	v_add_f32_e32 v2, v34, v2
	v_exp_f32_e32 v43, v12
	v_sub_f32_e32 v12, v42, v0
	v_add_f32_e32 v2, v35, v2
	v_exp_f32_e32 v42, v12
	v_add_f32_e32 v2, v41, v2
	v_add_f32_e32 v2, v40, v2
	v_add_f32_e32 v2, v43, v2
	v_add_f32_e32 v2, v42, v2
	ds_bpermute_b32 v12, v69, v2
	v_sub_f32_e32 v0, v67, v0
	v_exp_f32_e32 v0, v0
	v_cvt_pk_bf16_f32 v16, v44, v44
	v_cvt_pk_bf16_f32 v17, v44, v44
	s_waitcnt lgkmcnt(0)
	v_add_f32_e32 v2, v2, v12
	ds_bpermute_b32 v12, v71, v2
	v_cvt_pk_bf16_f32 v18, v1, v3
	v_cvt_pk_bf16_f32 v19, v4, v5
	v_mov_b32_e32 v61, v63
	s_waitcnt lgkmcnt(0)
	v_add_f32_e32 v2, v2, v12
	v_add_f32_e32 v46, v0, v2
	v_cvt_pk_bf16_f32 v12, v6, v7
	v_cvt_pk_bf16_f32 v13, v8, v9
	v_cvt_pk_bf16_f32 v14, v10, v11
	v_cvt_pk_bf16_f32 v15, v36, v15
	v_cvt_pk_bf16_f32 v8, v37, v38
	v_cvt_pk_bf16_f32 v9, v39, v45
	v_cvt_pk_bf16_f32 v10, v20, v21
	v_div_scale_f32 v20, s[10:11], v46, v46, 1.0
	v_rcp_f32_e32 v21, v20
	v_cvt_pk_bf16_f32 v11, v22, v23
	v_cvt_pk_bf16_f32 v4, v24, v25
	v_cvt_pk_bf16_f32 v5, v26, v27
	v_cvt_pk_bf16_f32 v6, v28, v29
	v_cvt_pk_bf16_f32 v7, v30, v31
	s_nop 0
	v_fma_f32 v22, -v20, v21, 1.0
	v_fmac_f32_e32 v21, v22, v21
	v_div_scale_f32 v22, vcc, 1.0, v46, 1.0
	v_mul_f32_e32 v23, v22, v21
	v_fma_f32 v24, -v20, v23, v22
	v_cvt_pk_bf16_f32 v0, v32, v33
	v_cvt_pk_bf16_f32 v1, v34, v35
	v_cvt_pk_bf16_f32 v2, v41, v40
	v_cvt_pk_bf16_f32 v3, v43, v42
	v_fmac_f32_e32 v23, v24, v21
	ds_read2_b64 v[24:27], v55 offset0:8 offset1:12
	ds_read2_b64 v[28:31], v55 offset0:16 offset1:20
	s_waitcnt lgkmcnt(1)
	v_mfma_f32_16x16x32_bf16 v[24:27], v[24:27], v[16:19], 0
	v_fma_f32 v20, -v20, v23, v22
	v_div_fmas_f32 v20, v20, v21, v23
	v_div_fixup_f32 v22, v20, v46, 1.0
	s_waitcnt lgkmcnt(0)
	v_mfma_f32_16x16x32_bf16 v[24:27], v[28:31], v[12:15], v[24:27]
	ds_read2_b64 v[28:31], v55 offset0:24 offset1:28
	v_lshlrev_b64 v[20:21], 11, v[60:61]
	v_lshl_add_u64 v[20:21], v[52:53], 0, v[20:21]
	s_waitcnt lgkmcnt(0)
	v_mfma_f32_16x16x32_bf16 v[24:27], v[28:31], v[8:11], v[24:27]
	ds_read2_b64 v[28:31], v55 offset0:32 offset1:36
	s_waitcnt lgkmcnt(0)
	v_mfma_f32_16x16x32_bf16 v[24:27], v[28:31], v[4:7], v[24:27]
	ds_read2_b64 v[28:31], v55 offset0:40 offset1:44
	s_waitcnt lgkmcnt(0)
	v_mfma_f32_16x16x32_bf16 v[24:27], v[28:31], v[0:3], v[24:27]
	s_nop 7
	v_pk_mul_f32 v[24:25], v[24:25], v[22:23] op_sel_hi:[1,0]
	v_pk_mul_f32 v[26:27], v[26:27], v[22:23] op_sel_hi:[1,0]
	v_cvt_pk_bf16_f32 v24, v24, v25
	s_nop 0
	v_cvt_pk_bf16_f32 v25, v26, v27
	global_store_dwordx2 v[20:21], v[24:25], off
	ds_read2_b64 v[24:27], v56 offset0:40 offset1:44
	ds_read2_b64 v[28:31], v56 offset0:48 offset1:52
	s_waitcnt lgkmcnt(1)
	v_mfma_f32_16x16x32_bf16 v[24:27], v[24:27], v[16:19], 0
	s_waitcnt lgkmcnt(0)
	v_mfma_f32_16x16x32_bf16 v[24:27], v[28:31], v[12:15], v[24:27]
	ds_read2_b64 v[28:31], v56 offset0:56 offset1:60
	s_waitcnt lgkmcnt(0)
	v_mfma_f32_16x16x32_bf16 v[24:27], v[28:31], v[8:11], v[24:27]
	ds_read2_b64 v[28:31], v56 offset0:64 offset1:68
	s_waitcnt lgkmcnt(0)
	v_mfma_f32_16x16x32_bf16 v[24:27], v[28:31], v[4:7], v[24:27]
	ds_read2_b64 v[28:31], v56 offset0:72 offset1:76
	s_waitcnt lgkmcnt(0)
	v_mfma_f32_16x16x32_bf16 v[24:27], v[28:31], v[0:3], v[24:27]
	s_nop 7
	v_pk_mul_f32 v[24:25], v[22:23], v[24:25] op_sel_hi:[0,1]
	v_pk_mul_f32 v[26:27], v[22:23], v[26:27] op_sel_hi:[0,1]
	v_cvt_pk_bf16_f32 v24, v24, v25
	v_cvt_pk_bf16_f32 v25, v26, v27
	global_store_dwordx2 v[20:21], v[24:25], off offset:32
	ds_read2_b64 v[24:27], v57 offset0:72 offset1:76
	ds_read2_b64 v[28:31], v57 offset0:80 offset1:84
	s_waitcnt lgkmcnt(1)
	v_mfma_f32_16x16x32_bf16 v[24:27], v[24:27], v[16:19], 0
	s_waitcnt lgkmcnt(0)
	v_mfma_f32_16x16x32_bf16 v[24:27], v[28:31], v[12:15], v[24:27]
	ds_read2_b64 v[28:31], v57 offset0:88 offset1:92
	s_waitcnt lgkmcnt(0)
	v_mfma_f32_16x16x32_bf16 v[24:27], v[28:31], v[8:11], v[24:27]
	ds_read2_b64 v[28:31], v57 offset0:96 offset1:100
	s_waitcnt lgkmcnt(0)
	v_mfma_f32_16x16x32_bf16 v[24:27], v[28:31], v[4:7], v[24:27]
	ds_read2_b64 v[28:31], v57 offset0:104 offset1:108
	s_waitcnt lgkmcnt(0)
	v_mfma_f32_16x16x32_bf16 v[24:27], v[28:31], v[0:3], v[24:27]
	s_nop 7
	v_pk_mul_f32 v[24:25], v[22:23], v[24:25] op_sel_hi:[0,1]
	v_pk_mul_f32 v[26:27], v[22:23], v[26:27] op_sel_hi:[0,1]
	v_cvt_pk_bf16_f32 v24, v24, v25
	v_cvt_pk_bf16_f32 v25, v26, v27
	global_store_dwordx2 v[20:21], v[24:25], off offset:64
	ds_read2_b64 v[24:27], v58 offset0:104 offset1:108
	s_waitcnt lgkmcnt(0)
	v_mfma_f32_16x16x32_bf16 v[16:19], v[24:27], v[16:19], 0
	ds_read2_b64 v[24:27], v58 offset0:112 offset1:116
	s_waitcnt lgkmcnt(0)
	v_mfma_f32_16x16x32_bf16 v[12:15], v[24:27], v[12:15], v[16:19]
	s_nop 4
	ds_read2_b64 v[16:19], v58 offset0:120 offset1:124
	s_waitcnt lgkmcnt(0)
	v_mfma_f32_16x16x32_bf16 v[8:11], v[16:19], v[8:11], v[12:15]
	s_nop 2
	ds_read2_b64 v[12:15], v58 offset0:128 offset1:132
	s_waitcnt lgkmcnt(0)
	v_mfma_f32_16x16x32_bf16 v[4:7], v[12:15], v[4:7], v[8:11]
	s_nop 2
	ds_read2_b64 v[8:11], v58 offset0:136 offset1:140
	s_waitcnt lgkmcnt(0)
	v_mfma_f32_16x16x32_bf16 v[0:3], v[8:11], v[0:3], v[4:7]
	s_nop 7
	v_pk_mul_f32 v[0:1], v[22:23], v[0:1] op_sel_hi:[0,1]
	v_pk_mul_f32 v[2:3], v[22:23], v[2:3] op_sel_hi:[0,1]
	v_cvt_pk_bf16_f32 v0, v0, v1
	v_cvt_pk_bf16_f32 v1, v2, v3
	global_store_dwordx2 v[20:21], v[0:1], off offset:96
	s_barrier
	s_and_b32 s4, s2, 7
	s_lshl_b32 s4, s4, 5
	s_lshr_b32 s81, s2, 3
	s_add_i32 s81, s81, s4
	s_addk_i32 s81, 0x100
	s_branch .Lq_remap
